# fast loops: the softmax wave raises its priority to 1 for its last 17 instructions (conversions + row-sum update) so it reaches the barrier together with the MFMA wave
# baseline (speedup 1.0000x reference)
.Lfm_a_exp:
	v_exp_f32_e32 v34, v34
	v_exp_f32_e32 v50, v50
	v_exp_f32_e32 v35, v35
	v_exp_f32_e32 v51, v51
	v_exp_f32_e32 v42, v42
	v_exp_f32_e32 v58, v58
	v_exp_f32_e32 v43, v43
	v_exp_f32_e32 v59, v59
	v_exp_f32_e32 v36, v36
	v_exp_f32_e32 v52, v52
	v_exp_f32_e32 v37, v37
	v_exp_f32_e32 v53, v53
	v_exp_f32_e32 v44, v44
	v_exp_f32_e32 v60, v60
	v_exp_f32_e32 v45, v45
	v_exp_f32_e32 v61, v61
	v_exp_f32_e32 v38, v38
	v_exp_f32_e32 v54, v54
	v_exp_f32_e32 v39, v39
	v_exp_f32_e32 v55, v55
	v_exp_f32_e32 v46, v46
	v_exp_f32_e32 v62, v62
	v_exp_f32_e32 v47, v47
	v_exp_f32_e32 v63, v63
	v_exp_f32_e32 v40, v40
	v_exp_f32_e32 v56, v56
	v_exp_f32_e32 v41, v41
	v_exp_f32_e32 v57, v57
	v_exp_f32_e32 v48, v48
	v_exp_f32_e32 v64, v64
	v_exp_f32_e32 v49, v49
	v_exp_f32_e32 v65, v65
	v_pk_add_f32 v[122:123], v[34:35], v[50:51]
	v_pk_add_f32 v[124:125], v[36:37], v[52:53]
	v_pk_add_f32 v[126:127], v[38:39], v[54:55]
	v_pk_add_f32 v[128:129], v[40:41], v[56:57]
	v_pk_add_f32 v[130:131], v[42:43], v[58:59]
	v_pk_add_f32 v[132:133], v[44:45], v[60:61]
	v_pk_add_f32 v[134:135], v[46:47], v[62:63]
	v_pk_add_f32 v[136:137], v[48:49], v[64:65]
	v_pk_add_f32 v[122:123], v[122:123], v[124:125]
	v_pk_add_f32 v[126:127], v[126:127], v[128:129]
	v_pk_add_f32 v[130:131], v[130:131], v[132:133]
	v_pk_add_f32 v[134:135], v[134:135], v[136:137]
	v_pk_add_f32 v[122:123], v[122:123], v[126:127]
	v_pk_add_f32 v[130:131], v[130:131], v[134:135]
	v_pk_add_f32 v[122:123], v[122:123], v[130:131]
	v_add_f32_e32 v0, v122, v123
	s_setprio 1
	v_cvt_pk_bf16_f32 v122, v34, v35
	v_cvt_pk_bf16_f32 v123, v36, v37
	v_cvt_pk_bf16_f32 v124, v38, v39
	v_cvt_pk_bf16_f32 v125, v40, v41
	v_cvt_pk_bf16_f32 v126, v42, v43
	v_cvt_pk_bf16_f32 v127, v44, v45
	v_cvt_pk_bf16_f32 v128, v46, v47
	v_cvt_pk_bf16_f32 v129, v48, v49
	v_cvt_pk_bf16_f32 v130, v50, v51
	v_cvt_pk_bf16_f32 v131, v52, v53
	v_cvt_pk_bf16_f32 v132, v54, v55
	v_cvt_pk_bf16_f32 v133, v56, v57
	v_cvt_pk_bf16_f32 v134, v58, v59
	v_cvt_pk_bf16_f32 v135, v60, v61
	v_cvt_pk_bf16_f32 v136, v62, v63
	v_cvt_pk_bf16_f32 v137, v64, v65
	v_add_f32_e32 v162, v162, v0
	s_waitcnt lgkmcnt(0)
	s_barrier
	v_mfma_f32_32x32x16_bf16 v[2:17], v[164:167], v[122:125], v[2:17]
	s_setprio 1
	v_add3_u32 v0, s57, v152, v153
	s_waitcnt vmcnt(3)
	ds_write_b128 v0, v[86:89]
	v_mfma_f32_32x32x16_bf16 v[18:33], v[168:171], v[122:125], v[18:33]
	v_add3_u32 v0, s57, v154, v155
	ds_write_b128 v0, v[90:93]
	v_mfma_f32_32x32x16_bf16 v[2:17], v[172:175], v[126:129], v[2:17]
	v_add3_u32 v0, s57, v156, v140
	ds_write_b128 v0, v[82:85] offset:13312
	v_add_u32_e32 v249, s60, v157
	v_mfma_f32_32x32x16_bf16 v[18:33], v[176:179], v[126:129], v[18:33]
	ds_read_b128 v[236:239], v249
	ds_read_b128 v[240:243], v249 offset:6656
	ds_read_b128 v[244:247], v249 offset:32
	v_mfma_f32_32x32x16_bf16 v[2:17], v[180:183], v[130:133], v[2:17]
	ds_read_b128 v[164:167], v249 offset:6688
	ds_read_b128 v[168:171], v249 offset:64
	ds_read_b128 v[172:175], v249 offset:6720
	v_mfma_f32_32x32x16_bf16 v[18:33], v[220:223], v[130:133], v[18:33]
	ds_read_b128 v[176:179], v249 offset:96
	ds_read_b128 v[180:183], v249 offset:6752
	ds_read_b128 v[220:223], v249 offset:128
	v_mfma_f32_32x32x16_bf16 v[2:17], v[224:227], v[134:137], v[2:17]
	ds_read_b128 v[224:227], v249 offset:6784
	v_mfma_f32_32x32x16_bf16 v[18:33], v[232:235], v[134:137], v[18:33]
	ds_read_b128 v[232:235], v249 offset:160
	s_waitcnt lgkmcnt(9)
	v_mfma_f32_32x32x16_bf16 v[34:49], v[236:239], v[196:199], v[66:81]
	ds_read_b128 v[236:239], v249 offset:6816
	s_add_i32 s0, s59, 4
	s_lshl_b32 s8, s0, 6
	v_mfma_f32_32x32x16_bf16 v[50:65], v[240:243], v[196:199], v[66:81]
	s_mul_i32 s0, s8, 0x600
	s_mov_b32 s1, 0
	s_waitcnt lgkmcnt(7)
	v_mfma_f32_32x32x16_bf16 v[34:49], v[244:247], v[200:203], v[34:49]
	v_add_u32_e32 v248, s60, v160
	v_lshl_add_u64 v[82:83], s[0:1], 0, v[186:187]
	v_lshl_add_u64 v[84:85], s[0:1], 0, v[188:189]
	v_mfma_f32_32x32x16_bf16 v[50:65], v[164:167], v[200:203], v[50:65]
	ds_read_b128 v[164:167], v248 offset:13312
	global_load_dwordx4 v[86:89], v[82:83], off
	global_load_dwordx4 v[90:93], v[84:85], off
	v_lshl_add_u64 v[82:83], s[8:9], 1, v[142:143]
	v_mfma_f32_32x32x16_bf16 v[34:49], v[168:171], v[204:207], v[34:49]
	ds_read_b128 v[168:171], v248 offset:17920
	global_load_dwordx4 v[82:85], v[82:83], off
	s_waitcnt lgkmcnt(6)
	v_mfma_f32_32x32x16_bf16 v[50:65], v[172:175], v[204:207], v[50:65]
	ds_read_b128 v[172:175], v248 offset:13344
	v_mfma_f32_32x32x16_bf16 v[34:49], v[176:179], v[208:211], v[34:49]
	ds_read_b128 v[176:179], v248 offset:17952
	v_mfma_f32_32x32x16_bf16 v[50:65], v[180:183], v[208:211], v[50:65]
	ds_read_b128 v[180:183], v248 offset:13376
	s_waitcnt lgkmcnt(6)
	v_mfma_f32_32x32x16_bf16 v[34:49], v[220:223], v[212:215], v[34:49]
	ds_read_b128 v[220:223], v248 offset:17984
	v_mfma_f32_32x32x16_bf16 v[50:65], v[224:227], v[212:215], v[50:65]
	ds_read_b128 v[224:227], v248 offset:13408
	v_mfma_f32_32x32x16_bf16 v[34:49], v[232:235], v[216:219], v[34:49]
	ds_read_b128 v[232:235], v248 offset:18016
	s_waitcnt lgkmcnt(8)
	v_mfma_f32_32x32x16_bf16 v[50:65], v[236:239], v[216:219], v[50:65]
	s_setprio 0
	s_waitcnt lgkmcnt(8)
	s_barrier
	v_max3_f32 v0, v34, v35, v36
	v_max3_f32 v106, v50, v51, v52
	v_max3_f32 v0, v0, v37, v38
	v_max3_f32 v106, v106, v53, v54
	v_max3_f32 v0, v0, v39, v40
	v_max3_f32 v106, v106, v55, v56
	v_max3_f32 v0, v0, v41, v42
	v_max3_f32 v106, v106, v57, v58
	v_max3_f32 v0, v0, v43, v44
	v_max3_f32 v106, v106, v59, v60
	v_max3_f32 v0, v0, v45, v46
	v_max3_f32 v106, v106, v61, v62
	v_max3_f32 v0, v0, v47, v48
	v_max3_f32 v106, v106, v63, v64
	v_max3_f32 v0, v0, v106, v49
	v_max_f32_e32 v0, v0, v65
	v_cmp_lt_f32_e32 vcc, s35, v0
	s_cbranch_vccnz .Lfm_b_resc
.Lfm_b_exp:
	v_exp_f32_e32 v34, v34
	v_exp_f32_e32 v50, v50
	v_exp_f32_e32 v35, v35
	v_exp_f32_e32 v51, v51
	v_exp_f32_e32 v42, v42
	v_exp_f32_e32 v58, v58
	v_exp_f32_e32 v43, v43
	v_exp_f32_e32 v59, v59
	v_exp_f32_e32 v36, v36
	v_exp_f32_e32 v52, v52
	v_exp_f32_e32 v37, v37
	v_exp_f32_e32 v53, v53
	v_exp_f32_e32 v44, v44
	v_exp_f32_e32 v60, v60
	v_exp_f32_e32 v45, v45
	v_exp_f32_e32 v61, v61
	v_exp_f32_e32 v38, v38
	v_exp_f32_e32 v54, v54
	v_exp_f32_e32 v39, v39
	v_exp_f32_e32 v55, v55
	v_exp_f32_e32 v46, v46
	v_exp_f32_e32 v62, v62
	v_exp_f32_e32 v47, v47
	v_exp_f32_e32 v63, v63
	v_exp_f32_e32 v40, v40
	v_exp_f32_e32 v56, v56
	v_exp_f32_e32 v41, v41
	v_exp_f32_e32 v57, v57
	v_exp_f32_e32 v48, v48
	v_exp_f32_e32 v64, v64
	v_exp_f32_e32 v49, v49
	v_exp_f32_e32 v65, v65
	v_pk_add_f32 v[106:107], v[34:35], v[50:51]
	v_pk_add_f32 v[108:109], v[36:37], v[52:53]
	v_pk_add_f32 v[110:111], v[38:39], v[54:55]
	v_pk_add_f32 v[112:113], v[40:41], v[56:57]
	v_pk_add_f32 v[114:115], v[42:43], v[58:59]
	v_pk_add_f32 v[116:117], v[44:45], v[60:61]
	v_pk_add_f32 v[118:119], v[46:47], v[62:63]
	v_pk_add_f32 v[120:121], v[48:49], v[64:65]
	v_pk_add_f32 v[106:107], v[106:107], v[108:109]
	v_pk_add_f32 v[110:111], v[110:111], v[112:113]
	v_pk_add_f32 v[114:115], v[114:115], v[116:117]
	v_pk_add_f32 v[118:119], v[118:119], v[120:121]
	v_pk_add_f32 v[106:107], v[106:107], v[110:111]
	v_pk_add_f32 v[114:115], v[114:115], v[118:119]
	v_pk_add_f32 v[106:107], v[106:107], v[114:115]
	v_add_f32_e32 v0, v106, v107
	s_setprio 1
	v_cvt_pk_bf16_f32 v106, v34, v35
	v_cvt_pk_bf16_f32 v107, v36, v37
	v_cvt_pk_bf16_f32 v108, v38, v39
	v_cvt_pk_bf16_f32 v109, v40, v41
	v_cvt_pk_bf16_f32 v110, v42, v43
	v_cvt_pk_bf16_f32 v111, v44, v45
	v_cvt_pk_bf16_f32 v112, v46, v47
	v_cvt_pk_bf16_f32 v113, v48, v49
	v_cvt_pk_bf16_f32 v114, v50, v51
	v_cvt_pk_bf16_f32 v115, v52, v53
	v_cvt_pk_bf16_f32 v116, v54, v55
	v_cvt_pk_bf16_f32 v117, v56, v57
	v_cvt_pk_bf16_f32 v118, v58, v59
	v_cvt_pk_bf16_f32 v119, v60, v61
	v_cvt_pk_bf16_f32 v120, v62, v63
	v_cvt_pk_bf16_f32 v121, v64, v65
	v_add_f32_e32 v162, v162, v0
	s_waitcnt lgkmcnt(0)
	s_barrier
	v_mfma_f32_32x32x16_bf16 v[2:17], v[164:167], v[106:109], v[2:17]
	s_setprio 1
	v_add3_u32 v0, s58, v152, v153
	s_waitcnt vmcnt(3)
	ds_write_b128 v0, v[98:101]
	v_mfma_f32_32x32x16_bf16 v[18:33], v[168:171], v[106:109], v[18:33]
	v_add3_u32 v0, s58, v154, v155
	ds_write_b128 v0, v[94:97]
	v_mfma_f32_32x32x16_bf16 v[2:17], v[172:175], v[110:113], v[2:17]
	v_add3_u32 v0, s58, v156, v140
	ds_write_b128 v0, v[102:105] offset:13312
	v_add_u32_e32 v249, s57, v157
	v_mfma_f32_32x32x16_bf16 v[18:33], v[176:179], v[110:113], v[18:33]
	ds_read_b128 v[236:239], v249
	ds_read_b128 v[240:243], v249 offset:6656
	ds_read_b128 v[244:247], v249 offset:32
	v_mfma_f32_32x32x16_bf16 v[2:17], v[180:183], v[114:117], v[2:17]
	ds_read_b128 v[164:167], v249 offset:6688
	ds_read_b128 v[168:171], v249 offset:64
	ds_read_b128 v[172:175], v249 offset:6720
	v_mfma_f32_32x32x16_bf16 v[18:33], v[220:223], v[114:117], v[18:33]
	ds_read_b128 v[176:179], v249 offset:96
	ds_read_b128 v[180:183], v249 offset:6752
	ds_read_b128 v[220:223], v249 offset:128
	v_mfma_f32_32x32x16_bf16 v[2:17], v[224:227], v[118:121], v[2:17]
	ds_read_b128 v[224:227], v249 offset:6784
	s_add_i32 s59, s59, 2
	s_mov_b32 s0, s58
	v_mfma_f32_32x32x16_bf16 v[18:33], v[232:235], v[118:121], v[18:33]
	ds_read_b128 v[232:235], v249 offset:160
	s_mov_b32 s58, s57
	s_mov_b32 s57, s60
	s_mov_b32 s60, s0
	s_addk_i32 s54, 0x80
	s_waitcnt lgkmcnt(9)
	v_mfma_f32_32x32x16_bf16 v[34:49], v[236:239], v[196:199], v[66:81]
	ds_read_b128 v[236:239], v249 offset:6816
	s_add_i32 s1, s59, 3
	s_lshl_b32 s8, s1, 6
	v_mfma_f32_32x32x16_bf16 v[50:65], v[240:243], v[196:199], v[66:81]
	s_mul_i32 s20, s8, 0x600
	s_mov_b32 s21, 0
	s_waitcnt lgkmcnt(7)
	v_mfma_f32_32x32x16_bf16 v[34:49], v[244:247], v[200:203], v[34:49]
	v_add_u32_e32 v248, s58, v160
	v_lshl_add_u64 v[94:95], s[20:21], 0, v[186:187]
	v_lshl_add_u64 v[96:97], s[20:21], 0, v[188:189]
	v_mfma_f32_32x32x16_bf16 v[50:65], v[164:167], v[200:203], v[50:65]
	ds_read_b128 v[164:167], v248 offset:13312
	v_lshl_add_u64 v[102:103], s[8:9], 1, v[142:143]
	global_load_dwordx4 v[98:101], v[94:95], off
	s_nop 0
	v_mfma_f32_32x32x16_bf16 v[34:49], v[168:171], v[204:207], v[34:49]
	ds_read_b128 v[168:171], v248 offset:17920
	global_load_dwordx4 v[94:97], v[96:97], off
	global_load_dwordx4 v[102:105], v[102:103], off
	s_waitcnt lgkmcnt(6)
	v_mfma_f32_32x32x16_bf16 v[50:65], v[172:175], v[204:207], v[50:65]
	ds_read_b128 v[172:175], v248 offset:13344
	v_mfma_f32_32x32x16_bf16 v[34:49], v[176:179], v[208:211], v[34:49]
	ds_read_b128 v[176:179], v248 offset:17952
	v_mfma_f32_32x32x16_bf16 v[50:65], v[180:183], v[208:211], v[50:65]
	ds_read_b128 v[180:183], v248 offset:13376
	s_waitcnt lgkmcnt(6)
	v_mfma_f32_32x32x16_bf16 v[34:49], v[220:223], v[212:215], v[34:49]
	ds_read_b128 v[220:223], v248 offset:17984
	v_mfma_f32_32x32x16_bf16 v[50:65], v[224:227], v[212:215], v[50:65]
	ds_read_b128 v[224:227], v248 offset:13408
	v_mfma_f32_32x32x16_bf16 v[34:49], v[232:235], v[216:219], v[34:49]
	ds_read_b128 v[232:235], v248 offset:18016
	s_waitcnt lgkmcnt(8)
	v_mfma_f32_32x32x16_bf16 v[50:65], v[236:239], v[216:219], v[50:65]
	s_setprio 0
	s_add_i32 s4, s55, s59
	s_cmp_lt_i32 s4, -1
	s_waitcnt lgkmcnt(8)
	s_barrier
	s_cbranch_scc1 .Lfm_head
	s_mov_b32 s0, s58
	s_mov_b32 s58, s60
	s_branch .LBB0_1037

.Lfd_a_exp:
	v_exp_f32_e32 v80, v80
	v_exp_f32_e32 v96, v96
	v_exp_f32_e32 v81, v81
	v_exp_f32_e32 v97, v97
	v_exp_f32_e32 v88, v88
	v_exp_f32_e32 v104, v104
	v_exp_f32_e32 v89, v89
	v_exp_f32_e32 v105, v105
	v_exp_f32_e32 v82, v82
	v_exp_f32_e32 v98, v98
	v_exp_f32_e32 v83, v83
	v_exp_f32_e32 v99, v99
	v_exp_f32_e32 v90, v90
	v_exp_f32_e32 v106, v106
	v_exp_f32_e32 v91, v91
	v_exp_f32_e32 v107, v107
	v_exp_f32_e32 v84, v84
	v_exp_f32_e32 v100, v100
	v_exp_f32_e32 v85, v85
	v_exp_f32_e32 v101, v101
	v_exp_f32_e32 v92, v92
	v_exp_f32_e32 v108, v108
	v_exp_f32_e32 v93, v93
	v_exp_f32_e32 v109, v109
	v_exp_f32_e32 v86, v86
	v_exp_f32_e32 v102, v102
	v_exp_f32_e32 v87, v87
	v_exp_f32_e32 v103, v103
	v_exp_f32_e32 v94, v94
	v_exp_f32_e32 v110, v110
	v_exp_f32_e32 v95, v95
	v_exp_f32_e32 v111, v111
	v_pk_add_f32 v[156:157], v[80:81], v[96:97]
	v_pk_add_f32 v[158:159], v[82:83], v[98:99]
	v_pk_add_f32 v[160:161], v[84:85], v[100:101]
	v_pk_add_f32 v[162:163], v[86:87], v[102:103]
	v_pk_add_f32 v[164:165], v[88:89], v[104:105]
	v_pk_add_f32 v[166:167], v[90:91], v[106:107]
	v_pk_add_f32 v[168:169], v[92:93], v[108:109]
	v_pk_add_f32 v[170:171], v[94:95], v[110:111]
	v_pk_add_f32 v[156:157], v[156:157], v[158:159]
	v_pk_add_f32 v[160:161], v[160:161], v[162:163]
	v_pk_add_f32 v[164:165], v[164:165], v[166:167]
	v_pk_add_f32 v[168:169], v[168:169], v[170:171]
	v_pk_add_f32 v[156:157], v[156:157], v[160:161]
	v_pk_add_f32 v[164:165], v[164:165], v[168:169]
	v_pk_add_f32 v[156:157], v[156:157], v[164:165]
	v_add_f32_e32 v0, v156, v157
	s_setprio 1
	v_cvt_pk_bf16_f32 v156, v80, v81
	v_cvt_pk_bf16_f32 v157, v82, v83
	v_cvt_pk_bf16_f32 v158, v84, v85
	v_cvt_pk_bf16_f32 v159, v86, v87
	v_cvt_pk_bf16_f32 v160, v88, v89
	v_cvt_pk_bf16_f32 v161, v90, v91
	v_cvt_pk_bf16_f32 v162, v92, v93
	v_cvt_pk_bf16_f32 v163, v94, v95
	v_cvt_pk_bf16_f32 v164, v96, v97
	v_cvt_pk_bf16_f32 v165, v98, v99
	v_cvt_pk_bf16_f32 v166, v100, v101
	v_cvt_pk_bf16_f32 v167, v102, v103
	v_cvt_pk_bf16_f32 v168, v104, v105
	v_cvt_pk_bf16_f32 v169, v106, v107
	v_cvt_pk_bf16_f32 v170, v108, v109
	v_cvt_pk_bf16_f32 v171, v110, v111
	v_add_f32_e32 v193, v193, v0
	s_waitcnt lgkmcnt(0)
	s_barrier
	v_mfma_f32_32x32x16_bf16 v[64:79], v[196:199], v[156:159], v[64:79]
	s_setprio 1
	v_add_u32_e32 v14, s50, v188
	s_waitcnt vmcnt(3)
	ds_write_b128 v14, v[136:139]
	v_mfma_f32_32x32x16_bf16 v[48:63], v[200:203], v[156:159], v[48:63]
	ds_read_b128 v[196:199], v248 offset:9280
	v_add_u32_e32 v14, s50, v186
	v_add_u32_e32 v15, v14, v175
	v_mfma_f32_32x32x16_bf16 v[32:47], v[204:207], v[156:159], v[32:47]
	ds_read_b128 v[200:203], v248 offset:13888
	v_add_u32_e32 v14, v14, v187
	ds_write_b128 v15, v[128:131] offset:9216
	v_mfma_f32_32x32x16_bf16 v[16:31], v[208:211], v[156:159], v[16:31]
	ds_read_b128 v[204:207], v248 offset:18496
	ds_write_b128 v14, v[132:135] offset:9216
	v_mfma_f32_32x32x16_bf16 v[64:79], v[212:215], v[160:163], v[64:79]
	ds_read_b128 v[208:211], v248 offset:23104
	v_add_u32_e32 v249, s55, v190
	v_mfma_f32_32x32x16_bf16 v[48:63], v[216:219], v[160:163], v[48:63]
	ds_read_b128 v[212:215], v248 offset:9312
	v_mfma_f32_32x32x16_bf16 v[32:47], v[220:223], v[160:163], v[32:47]
	ds_read_b128 v[216:219], v248 offset:13920
	v_mfma_f32_32x32x16_bf16 v[16:31], v[224:227], v[160:163], v[16:31]
	ds_read_b128 v[220:223], v248 offset:18528
	ds_read_b128 v[224:227], v248 offset:23136
	s_waitcnt lgkmcnt(4)
	v_mfma_f32_32x32x16_bf16 v[64:79], v[196:199], v[164:167], v[64:79]
	ds_read_b128 v[196:199], v249
	s_add_i32 s0, s54, 4
	s_lshl_b32 s8, s0, 6
	v_mfma_f32_32x32x16_bf16 v[48:63], v[200:203], v[164:167], v[48:63]
	ds_read_b128 v[200:203], v249 offset:4608
	v_add_u32_e32 v14, s8, v174
	v_ashrrev_i32_e32 v15, 31, v14
	v_mfma_f32_32x32x16_bf16 v[32:47], v[204:207], v[164:167], v[32:47]
	ds_read_b128 v[204:207], v249 offset:32
	v_lshlrev_b64 v[14:15], 10, v[14:15]
	v_lshl_add_u64 v[132:133], s[8:9], 1, v[176:177]
	v_mfma_f32_32x32x16_bf16 v[16:31], v[208:211], v[164:167], v[16:31]
	ds_read_b128 v[208:211], v249 offset:4640
	v_lshl_add_u64 v[14:15], v[182:183], 0, v[14:15]
	v_lshl_add_u64 v[128:129], v[132:133], 0, v[178:179]
	s_waitcnt lgkmcnt(4)
	v_mfma_f32_32x32x16_bf16 v[64:79], v[212:215], v[168:171], v[64:79]
	ds_read_b128 v[212:215], v249 offset:64
	global_load_dwordx4 v[136:139], v[14:15], off
	s_nop 0
	v_mfma_f32_32x32x16_bf16 v[48:63], v[216:219], v[168:171], v[48:63]
	ds_read_b128 v[216:219], v249 offset:4672
	global_load_dwordx4 v[128:131], v[128:129], off
	v_lshl_add_u64 v[14:15], v[132:133], 0, v[180:181]
	v_mfma_f32_32x32x16_bf16 v[32:47], v[220:223], v[168:171], v[32:47]
	ds_read_b128 v[220:223], v249 offset:96
	global_load_dwordx4 v[132:135], v[14:15], off
	v_mfma_f32_32x32x16_bf16 v[16:31], v[224:227], v[168:171], v[16:31]
	ds_read_b128 v[224:227], v249 offset:4704
	v_add_u32_e32 v248, s55, v190
	s_waitcnt lgkmcnt(4)
	v_mfma_f32_32x32x16_bf16 v[80:95], v[196:199], v[232:235], v[112:127]
	ds_read_b128 v[196:199], v248 offset:9216
	v_mfma_f32_32x32x16_bf16 v[96:111], v[200:203], v[232:235], v[112:127]
	ds_read_b128 v[200:203], v248 offset:13824
	v_mfma_f32_32x32x16_bf16 v[80:95], v[204:207], v[236:239], v[80:95]
	ds_read_b128 v[204:207], v248 offset:18432
	v_mfma_f32_32x32x16_bf16 v[96:111], v[208:211], v[236:239], v[96:111]
	ds_read_b128 v[208:211], v248 offset:23040
	s_waitcnt lgkmcnt(4)
	v_mfma_f32_32x32x16_bf16 v[80:95], v[212:215], v[240:243], v[80:95]
	ds_read_b128 v[212:215], v248 offset:9248
	v_mfma_f32_32x32x16_bf16 v[96:111], v[216:219], v[240:243], v[96:111]
	ds_read_b128 v[216:219], v248 offset:13856
	v_mfma_f32_32x32x16_bf16 v[80:95], v[220:223], v[244:247], v[80:95]
	ds_read_b128 v[220:223], v248 offset:18464
	v_mfma_f32_32x32x16_bf16 v[96:111], v[224:227], v[244:247], v[96:111]
	ds_read_b128 v[224:227], v248 offset:23072
	s_setprio 0
	s_waitcnt lgkmcnt(8)
	s_barrier
	v_max3_f32 v14, v80, v81, v82
	v_max3_f32 v15, v96, v97, v98
	v_max3_f32 v14, v14, v83, v84
	v_max3_f32 v15, v15, v99, v100
	v_max3_f32 v14, v14, v85, v86
	v_max3_f32 v15, v15, v101, v102
	v_max3_f32 v14, v14, v87, v88
	v_max3_f32 v15, v15, v103, v104
	v_max3_f32 v14, v14, v89, v90
	v_max3_f32 v15, v15, v105, v106
	v_max3_f32 v14, v14, v91, v92
	v_max3_f32 v15, v15, v107, v108
	v_max3_f32 v14, v14, v93, v94
	v_max3_f32 v15, v15, v109, v110
	v_max3_f32 v14, v14, v15, v95
	v_max_f32_e32 v14, v14, v111
	v_cmp_lt_f32_e32 vcc, s33, v14
	s_cbranch_vccnz .Lfd_b_resc
.Lfd_b_exp:
	v_exp_f32_e32 v80, v80
	v_exp_f32_e32 v96, v96
	v_exp_f32_e32 v81, v81
	v_exp_f32_e32 v97, v97
	v_exp_f32_e32 v88, v88
	v_exp_f32_e32 v104, v104
	v_exp_f32_e32 v89, v89
	v_exp_f32_e32 v105, v105
	v_exp_f32_e32 v82, v82
	v_exp_f32_e32 v98, v98
	v_exp_f32_e32 v83, v83
	v_exp_f32_e32 v99, v99
	v_exp_f32_e32 v90, v90
	v_exp_f32_e32 v106, v106
	v_exp_f32_e32 v91, v91
	v_exp_f32_e32 v107, v107
	v_exp_f32_e32 v84, v84
	v_exp_f32_e32 v100, v100
	v_exp_f32_e32 v85, v85
	v_exp_f32_e32 v101, v101
	v_exp_f32_e32 v92, v92
	v_exp_f32_e32 v108, v108
	v_exp_f32_e32 v93, v93
	v_exp_f32_e32 v109, v109
	v_exp_f32_e32 v86, v86
	v_exp_f32_e32 v102, v102
	v_exp_f32_e32 v87, v87
	v_exp_f32_e32 v103, v103
	v_exp_f32_e32 v94, v94
	v_exp_f32_e32 v110, v110
	v_exp_f32_e32 v95, v95
	v_exp_f32_e32 v111, v111
	v_pk_add_f32 v[140:141], v[80:81], v[96:97]
	v_pk_add_f32 v[142:143], v[82:83], v[98:99]
	v_pk_add_f32 v[144:145], v[84:85], v[100:101]
	v_pk_add_f32 v[146:147], v[86:87], v[102:103]
	v_pk_add_f32 v[148:149], v[88:89], v[104:105]
	v_pk_add_f32 v[150:151], v[90:91], v[106:107]
	v_pk_add_f32 v[152:153], v[92:93], v[108:109]
	v_pk_add_f32 v[154:155], v[94:95], v[110:111]
	v_pk_add_f32 v[140:141], v[140:141], v[142:143]
	v_pk_add_f32 v[144:145], v[144:145], v[146:147]
	v_pk_add_f32 v[148:149], v[148:149], v[150:151]
	v_pk_add_f32 v[152:153], v[152:153], v[154:155]
	v_pk_add_f32 v[140:141], v[140:141], v[144:145]
	v_pk_add_f32 v[148:149], v[148:149], v[152:153]
	v_pk_add_f32 v[140:141], v[140:141], v[148:149]
	v_add_f32_e32 v14, v140, v141
	s_setprio 1
	v_cvt_pk_bf16_f32 v140, v80, v81
	v_cvt_pk_bf16_f32 v141, v82, v83
	v_cvt_pk_bf16_f32 v142, v84, v85
	v_cvt_pk_bf16_f32 v143, v86, v87
	v_cvt_pk_bf16_f32 v144, v88, v89
	v_cvt_pk_bf16_f32 v145, v90, v91
	v_cvt_pk_bf16_f32 v146, v92, v93
	v_cvt_pk_bf16_f32 v147, v94, v95
	v_cvt_pk_bf16_f32 v148, v96, v97
	v_cvt_pk_bf16_f32 v149, v98, v99
	v_cvt_pk_bf16_f32 v150, v100, v101
	v_cvt_pk_bf16_f32 v151, v102, v103
	v_cvt_pk_bf16_f32 v152, v104, v105
	v_cvt_pk_bf16_f32 v153, v106, v107
	v_cvt_pk_bf16_f32 v154, v108, v109
	v_cvt_pk_bf16_f32 v155, v110, v111
	v_add_f32_e32 v193, v193, v14
	s_waitcnt lgkmcnt(0)
	s_barrier
	v_mfma_f32_32x32x16_bf16 v[64:79], v[196:199], v[140:143], v[64:79]
	s_setprio 1
	v_add_u32_e32 v0, s51, v188
	s_waitcnt vmcnt(3)
	ds_write_b128 v0, v[10:13]
	v_mfma_f32_32x32x16_bf16 v[48:63], v[200:203], v[140:143], v[48:63]
	ds_read_b128 v[196:199], v248 offset:9280
	v_add_u32_e32 v0, s51, v186
	v_add_u32_e32 v10, v0, v175
	v_mfma_f32_32x32x16_bf16 v[32:47], v[204:207], v[140:143], v[32:47]
	ds_read_b128 v[200:203], v248 offset:13888
	v_add_u32_e32 v0, v0, v187
	ds_write_b128 v10, v[2:5] offset:9216
	v_mfma_f32_32x32x16_bf16 v[16:31], v[208:211], v[140:143], v[16:31]
	ds_read_b128 v[204:207], v248 offset:18496
	ds_write_b128 v0, v[6:9] offset:9216
	v_mfma_f32_32x32x16_bf16 v[64:79], v[212:215], v[144:147], v[64:79]
	ds_read_b128 v[208:211], v248 offset:23104
	v_add_u32_e32 v249, s50, v190
	v_mfma_f32_32x32x16_bf16 v[48:63], v[216:219], v[144:147], v[48:63]
	ds_read_b128 v[212:215], v248 offset:9312
	s_add_i32 s54, s54, 2
	s_mov_b32 s0, s51
	v_mfma_f32_32x32x16_bf16 v[32:47], v[220:223], v[144:147], v[32:47]
	ds_read_b128 v[216:219], v248 offset:13920
	s_mov_b32 s51, s50
	s_mov_b32 s50, s55
	v_mfma_f32_32x32x16_bf16 v[16:31], v[224:227], v[144:147], v[16:31]
	ds_read_b128 v[220:223], v248 offset:18528
	ds_read_b128 v[224:227], v248 offset:23136
	s_mov_b32 s55, s0
	s_addk_i32 s47, 0x80
	s_waitcnt lgkmcnt(4)
	v_mfma_f32_32x32x16_bf16 v[64:79], v[196:199], v[148:151], v[64:79]
	ds_read_b128 v[196:199], v249
	s_add_i32 s1, s54, 3
	s_lshl_b32 s8, s1, 6
	v_mfma_f32_32x32x16_bf16 v[48:63], v[200:203], v[148:151], v[48:63]
	ds_read_b128 v[200:203], v249 offset:4608
	v_add_u32_e32 v2, s8, v174
	v_ashrrev_i32_e32 v3, 31, v2
	v_mfma_f32_32x32x16_bf16 v[32:47], v[204:207], v[148:151], v[32:47]
	ds_read_b128 v[204:207], v249 offset:32
	v_lshlrev_b64 v[2:3], 10, v[2:3]
	v_lshl_add_u64 v[6:7], s[8:9], 1, v[176:177]
	v_mfma_f32_32x32x16_bf16 v[16:31], v[208:211], v[148:151], v[16:31]
	ds_read_b128 v[208:211], v249 offset:4640
	v_lshl_add_u64 v[2:3], v[182:183], 0, v[2:3]
	v_lshl_add_u64 v[4:5], v[6:7], 0, v[178:179]
	s_waitcnt lgkmcnt(4)
	v_mfma_f32_32x32x16_bf16 v[64:79], v[212:215], v[152:155], v[64:79]
	ds_read_b128 v[212:215], v249 offset:64
	v_lshl_add_u64 v[6:7], v[6:7], 0, v[180:181]
	global_load_dwordx4 v[10:13], v[2:3], off
	v_mfma_f32_32x32x16_bf16 v[48:63], v[216:219], v[152:155], v[48:63]
	ds_read_b128 v[216:219], v249 offset:4672
	s_nop 0
	global_load_dwordx4 v[2:5], v[4:5], off
	v_mfma_f32_32x32x16_bf16 v[32:47], v[220:223], v[152:155], v[32:47]
	ds_read_b128 v[220:223], v249 offset:96
	global_load_dwordx4 v[6:9], v[6:7], off
	v_mfma_f32_32x32x16_bf16 v[16:31], v[224:227], v[152:155], v[16:31]
	ds_read_b128 v[224:227], v249 offset:4704
	v_add_u32_e32 v248, s51, v190
	s_waitcnt lgkmcnt(4)
	v_mfma_f32_32x32x16_bf16 v[80:95], v[196:199], v[232:235], v[112:127]
	ds_read_b128 v[196:199], v248 offset:9216
	v_mfma_f32_32x32x16_bf16 v[96:111], v[200:203], v[232:235], v[112:127]
	ds_read_b128 v[200:203], v248 offset:13824
	v_mfma_f32_32x32x16_bf16 v[80:95], v[204:207], v[236:239], v[80:95]
	ds_read_b128 v[204:207], v248 offset:18432
	v_mfma_f32_32x32x16_bf16 v[96:111], v[208:211], v[236:239], v[96:111]
	ds_read_b128 v[208:211], v248 offset:23040
	s_waitcnt lgkmcnt(4)
	v_mfma_f32_32x32x16_bf16 v[80:95], v[212:215], v[240:243], v[80:95]
	ds_read_b128 v[212:215], v248 offset:9248
	v_mfma_f32_32x32x16_bf16 v[96:111], v[216:219], v[240:243], v[96:111]
	ds_read_b128 v[216:219], v248 offset:13856
	s_add_i32 s4, s48, s54
	v_mfma_f32_32x32x16_bf16 v[80:95], v[220:223], v[244:247], v[80:95]
	ds_read_b128 v[220:223], v248 offset:18464
	v_mfma_f32_32x32x16_bf16 v[96:111], v[224:227], v[244:247], v[96:111]
	ds_read_b128 v[224:227], v248 offset:23072
	s_cmp_lt_i32 s4, -1
	s_setprio 0
	s_waitcnt lgkmcnt(8)
	s_barrier
	s_cbranch_scc1 .Lfd_head
	s_mov_b32 s0, s51
	s_mov_b32 s51, s55
	s_branch .LBB0_1072
